# hoist the 8 serialized ssq row-scale loads to the head of the GEMM epilogues (phases 1,3,8); one wait instead of eight
# speedup vs baseline: 1.0118x; 1.0118x over previous
.LBB0_176:
	v_lshl_add_u32 v164, s14, 8, v138
	v_ashrrev_i32_e32 v165, 31, v164
	v_lshl_add_u64 v[164:165], v[164:165], 2, s[84:85]
	global_load_dword v170, v[164:165], off
	global_load_dword v175, v[164:165], off offset:64
	global_load_dword v176, v[164:165], off offset:128
	global_load_dword v177, v[164:165], off offset:192
	global_load_dword v178, v[164:165], off offset:512
	global_load_dword v179, v[164:165], off offset:576
	global_load_dword v180, v[164:165], off offset:640
	global_load_dword v181, v[164:165], off offset:704
	s_lshl_b32 s9, s15, 1
	s_mul_i32 s14, s14, 44
	s_add_i32 s14, s14, s9
	s_or_b32 s14, s14, s53
	s_ashr_i32 s15, s14, 31
	s_lshl_b64 s[14:15], s[14:15], 15
	s_add_u32 s14, s80, s14
	s_addc_u32 s15, s81, s15
	s_waitcnt vmcnt(0)
	v_fmamk_f32 v170, v170, 0x3a800000, v169
	v_cmp_gt_f32_e32 vcc, s58, v170
	v_mul_f32_e32 v171, 0x4b800000, v170
	s_nop 0
	v_cndmask_b32_e32 v170, v170, v171, vcc
	v_rsq_f32_e32 v170, v170
	s_nop 0
	v_mul_f32_e32 v171, 0x45800000, v170
	v_cndmask_b32_e32 v170, v170, v171, vcc
	v_pk_mul_f32 v[124:125], v[124:125], v[170:171] op_sel_hi:[1,0]
	s_nop 0
	v_mul_f32_e32 v171, 0xbfb8aa3b, v124
	v_exp_f32_e32 v171, v171
	s_nop 0
	v_add_f32_e32 v171, 1.0, v171
	v_rcp_f32_e32 v172, v171
	v_pk_mul_f32 v[116:117], v[116:117], v[170:171] op_sel_hi:[1,0]
	v_mul_f32_e32 v171, 0xbfb8aa3b, v125
	v_exp_f32_e32 v171, v171
	s_nop 0
	v_add_f32_e32 v171, 1.0, v171
	v_rcp_f32_e32 v173, v171
	v_pk_mul_f32 v[118:119], v[118:119], v[170:171] op_sel_hi:[1,0]
	v_pk_mul_f32 v[120:121], v[120:121], v[170:171] op_sel_hi:[1,0]
	v_pk_mul_f32 v[112:113], v[112:113], v[170:171] op_sel_hi:[1,0]
	v_pk_mul_f32 v[124:125], v[124:125], v[172:173]
	v_pk_mul_f32 v[114:115], v[114:115], v[170:171] op_sel_hi:[1,0]
	v_pk_mul_f32 v[116:117], v[116:117], v[124:125]
	v_pk_mul_f32 v[124:125], v[126:127], v[170:171] op_sel_hi:[1,0]
	s_nop 0
	v_mul_f32_e32 v126, 0xbfb8aa3b, v124
	v_mul_f32_e32 v127, 0xbfb8aa3b, v125
	v_exp_f32_e32 v126, v126
	v_exp_f32_e32 v127, v127
	v_add_f32_e32 v126, 1.0, v126
	v_add_f32_e32 v127, 1.0, v127
	v_rcp_f32_e32 v126, v126
	v_rcp_f32_e32 v127, v127
	s_nop 0
	v_pk_mul_f32 v[124:125], v[124:125], v[126:127]
	s_nop 0
	v_pk_mul_f32 v[118:119], v[118:119], v[124:125]
	v_mul_f32_e32 v124, 0xbfb8aa3b, v120
	v_mul_f32_e32 v125, 0xbfb8aa3b, v121
	v_exp_f32_e32 v124, v124
	v_exp_f32_e32 v125, v125
	v_add_f32_e32 v124, 1.0, v124
	v_add_f32_e32 v125, 1.0, v125
	v_rcp_f32_e32 v124, v124
	v_rcp_f32_e32 v125, v125
	s_nop 0
	v_pk_mul_f32 v[120:121], v[120:121], v[124:125]
	s_nop 0
	v_pk_mul_f32 v[120:121], v[112:113], v[120:121]
	v_pk_mul_f32 v[112:113], v[122:123], v[170:171] op_sel_hi:[1,0]
	s_nop 0
	v_mul_f32_e32 v122, 0xbfb8aa3b, v112
	v_mul_f32_e32 v123, 0xbfb8aa3b, v113
	v_exp_f32_e32 v122, v122
	v_exp_f32_e32 v123, v123
	v_add_f32_e32 v122, 1.0, v122
	v_add_f32_e32 v123, 1.0, v123
	v_rcp_f32_e32 v122, v122
	v_rcp_f32_e32 v123, v123
	s_nop 0
	v_pk_mul_f32 v[112:113], v[112:113], v[122:123]
	s_nop 0
	v_pk_mul_f32 v[122:123], v[114:115], v[112:113]
	v_cvt_pk_bf16_f32 v112, v116, v117
	v_lshl_add_u64 v[116:117], s[14:15], 0, v[140:141]
	v_cvt_pk_bf16_f32 v113, v118, v119
	v_cvt_pk_bf16_f32 v114, v120, v121
	v_cvt_pk_bf16_f32 v115, v122, v123
	v_lshl_add_u64 v[116:117], v[116:117], 0, v[136:137]
	global_store_dwordx4 v[116:117], v[112:115], off nt
	s_nop 1
	v_fmamk_f32 v112, v175, 0x3a800000, v169
	v_cmp_gt_f32_e32 vcc, s58, v112
	v_mul_f32_e32 v113, 0x4b800000, v112
	s_nop 0
	v_cndmask_b32_e32 v112, v112, v113, vcc
	v_rsq_f32_e32 v112, v112
	s_nop 0
	v_mul_f32_e32 v113, 0x45800000, v112
	v_cndmask_b32_e32 v112, v112, v113, vcc
	v_pk_mul_f32 v[108:109], v[108:109], v[112:113] op_sel_hi:[1,0]
	s_nop 0
	v_mul_f32_e32 v113, 0xbfb8aa3b, v108
	v_exp_f32_e32 v113, v113
	s_nop 0
	v_add_f32_e32 v113, 1.0, v113
	v_rcp_f32_e32 v114, v113
	v_pk_mul_f32 v[100:101], v[100:101], v[112:113] op_sel_hi:[1,0]
	v_mul_f32_e32 v113, 0xbfb8aa3b, v109
	v_exp_f32_e32 v113, v113
	s_nop 0
	v_add_f32_e32 v113, 1.0, v113
	v_rcp_f32_e32 v115, v113
	v_pk_mul_f32 v[102:103], v[102:103], v[112:113] op_sel_hi:[1,0]
	v_pk_mul_f32 v[104:105], v[104:105], v[112:113] op_sel_hi:[1,0]
	v_pk_mul_f32 v[96:97], v[96:97], v[112:113] op_sel_hi:[1,0]
	v_pk_mul_f32 v[108:109], v[108:109], v[114:115]
	v_pk_mul_f32 v[98:99], v[98:99], v[112:113] op_sel_hi:[1,0]
	v_pk_mul_f32 v[100:101], v[100:101], v[108:109]
	v_pk_mul_f32 v[108:109], v[110:111], v[112:113] op_sel_hi:[1,0]
	s_nop 0
	v_mul_f32_e32 v110, 0xbfb8aa3b, v108
	v_mul_f32_e32 v111, 0xbfb8aa3b, v109
	v_exp_f32_e32 v110, v110
	v_exp_f32_e32 v111, v111
	v_add_f32_e32 v110, 1.0, v110
	v_add_f32_e32 v111, 1.0, v111
	v_rcp_f32_e32 v110, v110
	v_rcp_f32_e32 v111, v111
	s_nop 0
	v_pk_mul_f32 v[108:109], v[108:109], v[110:111]
	s_nop 0
	v_pk_mul_f32 v[102:103], v[102:103], v[108:109]
	v_mul_f32_e32 v108, 0xbfb8aa3b, v104
	v_mul_f32_e32 v109, 0xbfb8aa3b, v105
	v_exp_f32_e32 v108, v108
	v_exp_f32_e32 v109, v109
	v_add_f32_e32 v108, 1.0, v108
	v_add_f32_e32 v109, 1.0, v109
	v_rcp_f32_e32 v108, v108
	v_rcp_f32_e32 v109, v109
	s_nop 0
	v_pk_mul_f32 v[104:105], v[104:105], v[108:109]
	s_nop 0
	v_pk_mul_f32 v[104:105], v[96:97], v[104:105]
	v_pk_mul_f32 v[96:97], v[106:107], v[112:113] op_sel_hi:[1,0]
	s_nop 0
	v_mul_f32_e32 v106, 0xbfb8aa3b, v96
	v_mul_f32_e32 v107, 0xbfb8aa3b, v97
	v_exp_f32_e32 v106, v106
	v_exp_f32_e32 v107, v107
	v_add_f32_e32 v106, 1.0, v106
	v_add_f32_e32 v107, 1.0, v107
	v_rcp_f32_e32 v106, v106
	v_rcp_f32_e32 v107, v107
	s_nop 0
	v_pk_mul_f32 v[96:97], v[96:97], v[106:107]
	s_nop 0
	v_pk_mul_f32 v[106:107], v[98:99], v[96:97]
	v_cvt_pk_bf16_f32 v96, v100, v101
	v_lshl_add_u64 v[100:101], s[14:15], 0, v[142:143]
	v_cvt_pk_bf16_f32 v97, v102, v103
	v_cvt_pk_bf16_f32 v98, v104, v105
	v_cvt_pk_bf16_f32 v99, v106, v107
	v_lshl_add_u64 v[100:101], v[100:101], 0, v[136:137]
	global_store_dwordx4 v[100:101], v[96:99], off nt
	s_nop 1
	v_fmamk_f32 v96, v176, 0x3a800000, v169
	v_cmp_gt_f32_e32 vcc, s58, v96
	v_mul_f32_e32 v97, 0x4b800000, v96
	s_nop 0
	v_cndmask_b32_e32 v96, v96, v97, vcc
	v_rsq_f32_e32 v96, v96
	s_nop 0
	v_mul_f32_e32 v97, 0x45800000, v96
	v_cndmask_b32_e32 v96, v96, v97, vcc
	v_pk_mul_f32 v[92:93], v[92:93], v[96:97] op_sel_hi:[1,0]
	s_nop 0
	v_mul_f32_e32 v97, 0xbfb8aa3b, v92
	v_exp_f32_e32 v97, v97
	s_nop 0
	v_add_f32_e32 v97, 1.0, v97
	v_rcp_f32_e32 v98, v97
	v_pk_mul_f32 v[84:85], v[84:85], v[96:97] op_sel_hi:[1,0]
	v_mul_f32_e32 v97, 0xbfb8aa3b, v93
	v_exp_f32_e32 v97, v97
	s_nop 0
	v_add_f32_e32 v97, 1.0, v97
	v_rcp_f32_e32 v99, v97
	v_pk_mul_f32 v[86:87], v[86:87], v[96:97] op_sel_hi:[1,0]
	v_pk_mul_f32 v[88:89], v[88:89], v[96:97] op_sel_hi:[1,0]
	v_pk_mul_f32 v[80:81], v[80:81], v[96:97] op_sel_hi:[1,0]
	v_pk_mul_f32 v[92:93], v[92:93], v[98:99]
	v_pk_mul_f32 v[82:83], v[82:83], v[96:97] op_sel_hi:[1,0]
	v_pk_mul_f32 v[84:85], v[84:85], v[92:93]
	v_pk_mul_f32 v[92:93], v[94:95], v[96:97] op_sel_hi:[1,0]
	s_nop 0
	v_mul_f32_e32 v94, 0xbfb8aa3b, v92
	v_mul_f32_e32 v95, 0xbfb8aa3b, v93
	v_exp_f32_e32 v94, v94
	v_exp_f32_e32 v95, v95
	v_add_f32_e32 v94, 1.0, v94
	v_add_f32_e32 v95, 1.0, v95
	v_rcp_f32_e32 v94, v94
	v_rcp_f32_e32 v95, v95
	s_nop 0
	v_pk_mul_f32 v[92:93], v[92:93], v[94:95]
	s_nop 0
	v_pk_mul_f32 v[86:87], v[86:87], v[92:93]
	v_mul_f32_e32 v92, 0xbfb8aa3b, v88
	v_mul_f32_e32 v93, 0xbfb8aa3b, v89
	v_exp_f32_e32 v92, v92
	v_exp_f32_e32 v93, v93
	v_add_f32_e32 v92, 1.0, v92
	v_add_f32_e32 v93, 1.0, v93
	v_rcp_f32_e32 v92, v92
	v_rcp_f32_e32 v93, v93
	s_nop 0
	v_pk_mul_f32 v[88:89], v[88:89], v[92:93]
	s_nop 0
	v_pk_mul_f32 v[88:89], v[80:81], v[88:89]
	v_pk_mul_f32 v[80:81], v[90:91], v[96:97] op_sel_hi:[1,0]
	s_nop 0
	v_mul_f32_e32 v90, 0xbfb8aa3b, v80
	v_mul_f32_e32 v91, 0xbfb8aa3b, v81
	v_exp_f32_e32 v90, v90
	v_exp_f32_e32 v91, v91
	v_add_f32_e32 v90, 1.0, v90
	v_add_f32_e32 v91, 1.0, v91
	v_rcp_f32_e32 v90, v90
	v_rcp_f32_e32 v91, v91
	s_nop 0
	v_pk_mul_f32 v[80:81], v[80:81], v[90:91]
	s_nop 0
	v_pk_mul_f32 v[90:91], v[82:83], v[80:81]
	v_cvt_pk_bf16_f32 v80, v84, v85
	v_lshl_add_u64 v[84:85], s[14:15], 0, v[144:145]
	v_cvt_pk_bf16_f32 v81, v86, v87
	v_cvt_pk_bf16_f32 v82, v88, v89
	v_cvt_pk_bf16_f32 v83, v90, v91
	v_lshl_add_u64 v[84:85], v[84:85], 0, v[136:137]
	global_store_dwordx4 v[84:85], v[80:83], off nt
	s_nop 1
	v_fmamk_f32 v80, v177, 0x3a800000, v169
	v_cmp_gt_f32_e32 vcc, s58, v80
	v_mul_f32_e32 v81, 0x4b800000, v80
	s_nop 0
	v_cndmask_b32_e32 v80, v80, v81, vcc
	v_rsq_f32_e32 v80, v80
	s_nop 0
	v_mul_f32_e32 v81, 0x45800000, v80
	v_cndmask_b32_e32 v80, v80, v81, vcc
	v_pk_mul_f32 v[76:77], v[76:77], v[80:81] op_sel_hi:[1,0]
	s_nop 0
	v_mul_f32_e32 v81, 0xbfb8aa3b, v76
	v_exp_f32_e32 v81, v81
	s_nop 0
	v_add_f32_e32 v81, 1.0, v81
	v_rcp_f32_e32 v82, v81
	v_pk_mul_f32 v[68:69], v[68:69], v[80:81] op_sel_hi:[1,0]
	v_mul_f32_e32 v81, 0xbfb8aa3b, v77
	v_exp_f32_e32 v81, v81
	s_nop 0
	v_add_f32_e32 v81, 1.0, v81
	v_rcp_f32_e32 v83, v81
	v_pk_mul_f32 v[70:71], v[70:71], v[80:81] op_sel_hi:[1,0]
	v_pk_mul_f32 v[72:73], v[72:73], v[80:81] op_sel_hi:[1,0]
	v_pk_mul_f32 v[64:65], v[64:65], v[80:81] op_sel_hi:[1,0]
	v_pk_mul_f32 v[76:77], v[76:77], v[82:83]
	v_pk_mul_f32 v[66:67], v[66:67], v[80:81] op_sel_hi:[1,0]
	v_pk_mul_f32 v[68:69], v[68:69], v[76:77]
	v_pk_mul_f32 v[76:77], v[78:79], v[80:81] op_sel_hi:[1,0]
	s_nop 0
	v_mul_f32_e32 v78, 0xbfb8aa3b, v76
	v_mul_f32_e32 v79, 0xbfb8aa3b, v77
	v_exp_f32_e32 v78, v78
	v_exp_f32_e32 v79, v79
	v_add_f32_e32 v78, 1.0, v78
	v_add_f32_e32 v79, 1.0, v79
	v_rcp_f32_e32 v78, v78
	v_rcp_f32_e32 v79, v79
	s_nop 0
	v_pk_mul_f32 v[76:77], v[76:77], v[78:79]
	s_nop 0
	v_pk_mul_f32 v[70:71], v[70:71], v[76:77]
	v_mul_f32_e32 v76, 0xbfb8aa3b, v72
	v_mul_f32_e32 v77, 0xbfb8aa3b, v73
	v_exp_f32_e32 v76, v76
	v_exp_f32_e32 v77, v77
	v_add_f32_e32 v76, 1.0, v76
	v_add_f32_e32 v77, 1.0, v77
	v_rcp_f32_e32 v76, v76
	v_rcp_f32_e32 v77, v77
	s_nop 0
	v_pk_mul_f32 v[72:73], v[72:73], v[76:77]
	s_nop 0
	v_pk_mul_f32 v[72:73], v[64:65], v[72:73]
	v_pk_mul_f32 v[64:65], v[74:75], v[80:81] op_sel_hi:[1,0]
	s_nop 0
	v_mul_f32_e32 v74, 0xbfb8aa3b, v64
	v_mul_f32_e32 v75, 0xbfb8aa3b, v65
	v_exp_f32_e32 v74, v74
	v_exp_f32_e32 v75, v75
	v_add_f32_e32 v74, 1.0, v74
	v_add_f32_e32 v75, 1.0, v75
	v_rcp_f32_e32 v74, v74
	v_rcp_f32_e32 v75, v75
	s_nop 0
	v_pk_mul_f32 v[64:65], v[64:65], v[74:75]
	s_nop 0
	v_pk_mul_f32 v[74:75], v[66:67], v[64:65]
	v_cvt_pk_bf16_f32 v64, v68, v69
	v_lshl_add_u64 v[68:69], s[14:15], 0, v[146:147]
	v_cvt_pk_bf16_f32 v65, v70, v71
	v_cvt_pk_bf16_f32 v66, v72, v73
	v_cvt_pk_bf16_f32 v67, v74, v75
	v_lshl_add_u64 v[68:69], v[68:69], 0, v[136:137]
	global_store_dwordx4 v[68:69], v[64:67], off nt
	s_nop 1
	v_fmamk_f32 v64, v178, 0x3a800000, v169
	v_cmp_gt_f32_e32 vcc, s58, v64
	v_mul_f32_e32 v65, 0x4b800000, v64
	s_nop 0
	v_cndmask_b32_e32 v64, v64, v65, vcc
	v_rsq_f32_e32 v64, v64
	s_nop 0
	v_mul_f32_e32 v65, 0x45800000, v64
	v_cndmask_b32_e32 v64, v64, v65, vcc
	v_pk_mul_f32 v[60:61], v[60:61], v[64:65] op_sel_hi:[1,0]
	s_nop 0
	v_mul_f32_e32 v65, 0xbfb8aa3b, v60
	v_exp_f32_e32 v65, v65
	s_nop 0
	v_add_f32_e32 v65, 1.0, v65
	v_rcp_f32_e32 v66, v65
	v_pk_mul_f32 v[52:53], v[52:53], v[64:65] op_sel_hi:[1,0]
	v_mul_f32_e32 v65, 0xbfb8aa3b, v61
	v_exp_f32_e32 v65, v65
	s_nop 0
	v_add_f32_e32 v65, 1.0, v65
	v_rcp_f32_e32 v67, v65
	v_pk_mul_f32 v[54:55], v[54:55], v[64:65] op_sel_hi:[1,0]
	v_pk_mul_f32 v[56:57], v[56:57], v[64:65] op_sel_hi:[1,0]
	v_pk_mul_f32 v[48:49], v[48:49], v[64:65] op_sel_hi:[1,0]
	v_pk_mul_f32 v[60:61], v[60:61], v[66:67]
	v_pk_mul_f32 v[50:51], v[50:51], v[64:65] op_sel_hi:[1,0]
	v_pk_mul_f32 v[52:53], v[52:53], v[60:61]
	v_pk_mul_f32 v[60:61], v[62:63], v[64:65] op_sel_hi:[1,0]
	s_nop 0
	v_mul_f32_e32 v62, 0xbfb8aa3b, v60
	v_mul_f32_e32 v63, 0xbfb8aa3b, v61
	v_exp_f32_e32 v62, v62
	v_exp_f32_e32 v63, v63
	v_add_f32_e32 v62, 1.0, v62
	v_add_f32_e32 v63, 1.0, v63
	v_rcp_f32_e32 v62, v62
	v_rcp_f32_e32 v63, v63
	s_nop 0
	v_pk_mul_f32 v[60:61], v[60:61], v[62:63]
	s_nop 0
	v_pk_mul_f32 v[54:55], v[54:55], v[60:61]
	v_mul_f32_e32 v60, 0xbfb8aa3b, v56
	v_mul_f32_e32 v61, 0xbfb8aa3b, v57
	v_exp_f32_e32 v60, v60
	v_exp_f32_e32 v61, v61
	v_add_f32_e32 v60, 1.0, v60
	v_add_f32_e32 v61, 1.0, v61
	v_rcp_f32_e32 v60, v60
	v_rcp_f32_e32 v61, v61
	s_nop 0
	v_pk_mul_f32 v[56:57], v[56:57], v[60:61]
	s_nop 0
	v_pk_mul_f32 v[56:57], v[48:49], v[56:57]
	v_pk_mul_f32 v[48:49], v[58:59], v[64:65] op_sel_hi:[1,0]
	s_nop 0
	v_mul_f32_e32 v58, 0xbfb8aa3b, v48
	v_mul_f32_e32 v59, 0xbfb8aa3b, v49
	v_exp_f32_e32 v58, v58
	v_exp_f32_e32 v59, v59
	v_add_f32_e32 v58, 1.0, v58
	v_add_f32_e32 v59, 1.0, v59
	v_rcp_f32_e32 v58, v58
	v_rcp_f32_e32 v59, v59
	s_nop 0
	v_pk_mul_f32 v[48:49], v[48:49], v[58:59]
	s_nop 0
	v_pk_mul_f32 v[58:59], v[50:51], v[48:49]
	v_cvt_pk_bf16_f32 v48, v52, v53
	v_lshl_add_u64 v[52:53], s[14:15], 0, v[148:149]
	v_cvt_pk_bf16_f32 v49, v54, v55
	v_cvt_pk_bf16_f32 v50, v56, v57
	v_cvt_pk_bf16_f32 v51, v58, v59
	v_lshl_add_u64 v[52:53], v[52:53], 0, v[136:137]
	global_store_dwordx4 v[52:53], v[48:51], off nt
	s_nop 1
	v_fmamk_f32 v48, v179, 0x3a800000, v169
	v_cmp_gt_f32_e32 vcc, s58, v48
	v_mul_f32_e32 v49, 0x4b800000, v48
	s_nop 0
	v_cndmask_b32_e32 v48, v48, v49, vcc
	v_rsq_f32_e32 v48, v48
	s_nop 0
	v_mul_f32_e32 v49, 0x45800000, v48
	v_cndmask_b32_e32 v48, v48, v49, vcc
	v_pk_mul_f32 v[44:45], v[44:45], v[48:49] op_sel_hi:[1,0]
	s_nop 0
	v_mul_f32_e32 v49, 0xbfb8aa3b, v44
	v_exp_f32_e32 v49, v49
	s_nop 0
	v_add_f32_e32 v49, 1.0, v49
	v_rcp_f32_e32 v50, v49
	v_pk_mul_f32 v[36:37], v[36:37], v[48:49] op_sel_hi:[1,0]
	v_mul_f32_e32 v49, 0xbfb8aa3b, v45
	v_exp_f32_e32 v49, v49
	s_nop 0
	v_add_f32_e32 v49, 1.0, v49
	v_rcp_f32_e32 v51, v49
	v_pk_mul_f32 v[38:39], v[38:39], v[48:49] op_sel_hi:[1,0]
	v_pk_mul_f32 v[40:41], v[40:41], v[48:49] op_sel_hi:[1,0]
	v_pk_mul_f32 v[32:33], v[32:33], v[48:49] op_sel_hi:[1,0]
	v_pk_mul_f32 v[44:45], v[44:45], v[50:51]
	v_pk_mul_f32 v[34:35], v[34:35], v[48:49] op_sel_hi:[1,0]
	v_pk_mul_f32 v[36:37], v[36:37], v[44:45]
	v_pk_mul_f32 v[44:45], v[46:47], v[48:49] op_sel_hi:[1,0]
	s_nop 0
	v_mul_f32_e32 v46, 0xbfb8aa3b, v44
	v_mul_f32_e32 v47, 0xbfb8aa3b, v45
	v_exp_f32_e32 v46, v46
	v_exp_f32_e32 v47, v47
	v_add_f32_e32 v46, 1.0, v46
	v_add_f32_e32 v47, 1.0, v47
	v_rcp_f32_e32 v46, v46
	v_rcp_f32_e32 v47, v47
	s_nop 0
	v_pk_mul_f32 v[44:45], v[44:45], v[46:47]
	s_nop 0
	v_pk_mul_f32 v[38:39], v[38:39], v[44:45]
	v_mul_f32_e32 v44, 0xbfb8aa3b, v40
	v_mul_f32_e32 v45, 0xbfb8aa3b, v41
	v_exp_f32_e32 v44, v44
	v_exp_f32_e32 v45, v45
	v_add_f32_e32 v44, 1.0, v44
	v_add_f32_e32 v45, 1.0, v45
	v_rcp_f32_e32 v44, v44
	v_rcp_f32_e32 v45, v45
	s_nop 0
	v_pk_mul_f32 v[40:41], v[40:41], v[44:45]
	s_nop 0
	v_pk_mul_f32 v[40:41], v[32:33], v[40:41]
	v_pk_mul_f32 v[32:33], v[42:43], v[48:49] op_sel_hi:[1,0]
	s_nop 0
	v_mul_f32_e32 v42, 0xbfb8aa3b, v32
	v_mul_f32_e32 v43, 0xbfb8aa3b, v33
	v_exp_f32_e32 v42, v42
	v_exp_f32_e32 v43, v43
	v_add_f32_e32 v42, 1.0, v42
	v_add_f32_e32 v43, 1.0, v43
	v_rcp_f32_e32 v42, v42
	v_rcp_f32_e32 v43, v43
	s_nop 0
	v_pk_mul_f32 v[32:33], v[32:33], v[42:43]
	s_nop 0
	v_pk_mul_f32 v[42:43], v[34:35], v[32:33]
	v_cvt_pk_bf16_f32 v32, v36, v37
	v_lshl_add_u64 v[36:37], s[14:15], 0, v[150:151]
	v_cvt_pk_bf16_f32 v33, v38, v39
	v_cvt_pk_bf16_f32 v34, v40, v41
	v_cvt_pk_bf16_f32 v35, v42, v43
	v_lshl_add_u64 v[36:37], v[36:37], 0, v[136:137]
	global_store_dwordx4 v[36:37], v[32:35], off nt
	s_nop 1
	v_fmamk_f32 v32, v180, 0x3a800000, v169
	v_cmp_gt_f32_e32 vcc, s58, v32
	v_mul_f32_e32 v33, 0x4b800000, v32
	s_nop 0
	v_cndmask_b32_e32 v32, v32, v33, vcc
	v_rsq_f32_e32 v32, v32
	s_nop 0
	v_mul_f32_e32 v33, 0x45800000, v32
	v_cndmask_b32_e32 v32, v32, v33, vcc
	v_pk_mul_f32 v[28:29], v[28:29], v[32:33] op_sel_hi:[1,0]
	s_nop 0
	v_mul_f32_e32 v33, 0xbfb8aa3b, v28
	v_exp_f32_e32 v33, v33
	s_nop 0
	v_add_f32_e32 v33, 1.0, v33
	v_rcp_f32_e32 v34, v33
	v_pk_mul_f32 v[20:21], v[20:21], v[32:33] op_sel_hi:[1,0]
	v_mul_f32_e32 v33, 0xbfb8aa3b, v29
	v_exp_f32_e32 v33, v33
	s_nop 0
	v_add_f32_e32 v33, 1.0, v33
	v_rcp_f32_e32 v35, v33
	v_pk_mul_f32 v[22:23], v[22:23], v[32:33] op_sel_hi:[1,0]
	v_pk_mul_f32 v[24:25], v[24:25], v[32:33] op_sel_hi:[1,0]
	v_pk_mul_f32 v[16:17], v[16:17], v[32:33] op_sel_hi:[1,0]
	v_pk_mul_f32 v[28:29], v[28:29], v[34:35]
	v_pk_mul_f32 v[18:19], v[18:19], v[32:33] op_sel_hi:[1,0]
	v_pk_mul_f32 v[20:21], v[20:21], v[28:29]
	v_pk_mul_f32 v[28:29], v[30:31], v[32:33] op_sel_hi:[1,0]
	s_nop 0
	v_mul_f32_e32 v30, 0xbfb8aa3b, v28
	v_mul_f32_e32 v31, 0xbfb8aa3b, v29
	v_exp_f32_e32 v30, v30
	v_exp_f32_e32 v31, v31
	v_add_f32_e32 v30, 1.0, v30
	v_add_f32_e32 v31, 1.0, v31
	v_rcp_f32_e32 v30, v30
	v_rcp_f32_e32 v31, v31
	s_nop 0
	v_pk_mul_f32 v[28:29], v[28:29], v[30:31]
	s_nop 0
	v_pk_mul_f32 v[22:23], v[22:23], v[28:29]
	v_mul_f32_e32 v28, 0xbfb8aa3b, v24
	v_mul_f32_e32 v29, 0xbfb8aa3b, v25
	v_exp_f32_e32 v28, v28
	v_exp_f32_e32 v29, v29
	v_add_f32_e32 v28, 1.0, v28
	v_add_f32_e32 v29, 1.0, v29
	v_rcp_f32_e32 v28, v28
	v_rcp_f32_e32 v29, v29
	s_nop 0
	v_pk_mul_f32 v[24:25], v[24:25], v[28:29]
	s_nop 0
	v_pk_mul_f32 v[24:25], v[16:17], v[24:25]
	v_pk_mul_f32 v[16:17], v[26:27], v[32:33] op_sel_hi:[1,0]
	s_nop 0
	v_mul_f32_e32 v26, 0xbfb8aa3b, v16
	v_mul_f32_e32 v27, 0xbfb8aa3b, v17
	v_exp_f32_e32 v26, v26
	v_exp_f32_e32 v27, v27
	v_add_f32_e32 v26, 1.0, v26
	v_add_f32_e32 v27, 1.0, v27
	v_rcp_f32_e32 v26, v26
	v_rcp_f32_e32 v27, v27
	s_nop 0
	v_pk_mul_f32 v[16:17], v[16:17], v[26:27]
	s_nop 0
	v_pk_mul_f32 v[26:27], v[18:19], v[16:17]
	v_cvt_pk_bf16_f32 v16, v20, v21
	v_lshl_add_u64 v[20:21], s[14:15], 0, v[152:153]
	v_cvt_pk_bf16_f32 v17, v22, v23
	v_cvt_pk_bf16_f32 v18, v24, v25
	v_cvt_pk_bf16_f32 v19, v26, v27
	v_lshl_add_u64 v[20:21], v[20:21], 0, v[136:137]
	global_store_dwordx4 v[20:21], v[16:19], off nt
	s_nop 1
	v_fmamk_f32 v16, v181, 0x3a800000, v169
	v_cmp_gt_f32_e32 vcc, s58, v16
	v_mul_f32_e32 v17, 0x4b800000, v16
	s_nop 0
	v_cndmask_b32_e32 v16, v16, v17, vcc
	v_rsq_f32_e32 v16, v16
	s_nop 0
	v_mul_f32_e32 v17, 0x45800000, v16
	v_cndmask_b32_e32 v16, v16, v17, vcc
	v_pk_mul_f32 v[12:13], v[12:13], v[16:17] op_sel_hi:[1,0]
	s_andn2_b64 vcc, exec, s[2:3]
	v_mul_f32_e32 v17, 0xbfb8aa3b, v12
	v_exp_f32_e32 v17, v17
	s_nop 0
	v_add_f32_e32 v17, 1.0, v17
	v_rcp_f32_e32 v18, v17
	v_pk_mul_f32 v[4:5], v[4:5], v[16:17] op_sel_hi:[1,0]
	v_mul_f32_e32 v17, 0xbfb8aa3b, v13
	v_exp_f32_e32 v17, v17
	s_nop 0
	v_add_f32_e32 v17, 1.0, v17
	v_rcp_f32_e32 v19, v17
	v_pk_mul_f32 v[6:7], v[6:7], v[16:17] op_sel_hi:[1,0]
	v_pk_mul_f32 v[8:9], v[8:9], v[16:17] op_sel_hi:[1,0]
	v_pk_mul_f32 v[0:1], v[0:1], v[16:17] op_sel_hi:[1,0]
	v_pk_mul_f32 v[12:13], v[12:13], v[18:19]
	v_pk_mul_f32 v[2:3], v[2:3], v[16:17] op_sel_hi:[1,0]
	v_pk_mul_f32 v[4:5], v[4:5], v[12:13]
	v_pk_mul_f32 v[12:13], v[14:15], v[16:17] op_sel_hi:[1,0]
	s_nop 0
	v_mul_f32_e32 v14, 0xbfb8aa3b, v12
	v_mul_f32_e32 v15, 0xbfb8aa3b, v13
	v_exp_f32_e32 v14, v14
	v_exp_f32_e32 v15, v15
	v_add_f32_e32 v14, 1.0, v14
	v_add_f32_e32 v15, 1.0, v15
	v_rcp_f32_e32 v14, v14
	v_rcp_f32_e32 v15, v15
	s_nop 0
	v_pk_mul_f32 v[12:13], v[12:13], v[14:15]
	s_nop 0
	v_pk_mul_f32 v[6:7], v[6:7], v[12:13]
	v_mul_f32_e32 v12, 0xbfb8aa3b, v8
	v_mul_f32_e32 v13, 0xbfb8aa3b, v9
	v_exp_f32_e32 v12, v12
	v_exp_f32_e32 v13, v13
	v_add_f32_e32 v12, 1.0, v12
	v_add_f32_e32 v13, 1.0, v13
	v_rcp_f32_e32 v12, v12
	v_rcp_f32_e32 v13, v13
	s_nop 0
	v_pk_mul_f32 v[8:9], v[8:9], v[12:13]
	s_nop 0
	v_pk_mul_f32 v[8:9], v[0:1], v[8:9]
	v_pk_mul_f32 v[0:1], v[10:11], v[16:17] op_sel_hi:[1,0]
	s_nop 0
	v_mul_f32_e32 v10, 0xbfb8aa3b, v0
	v_mul_f32_e32 v11, 0xbfb8aa3b, v1
	v_exp_f32_e32 v10, v10
	v_exp_f32_e32 v11, v11
	v_add_f32_e32 v10, 1.0, v10
	v_add_f32_e32 v11, 1.0, v11
	v_rcp_f32_e32 v10, v10
	v_rcp_f32_e32 v11, v11
	s_nop 0
	v_pk_mul_f32 v[0:1], v[0:1], v[10:11]
	s_nop 0
	v_pk_mul_f32 v[10:11], v[2:3], v[0:1]
	v_cvt_pk_bf16_f32 v0, v4, v5
	v_lshl_add_u64 v[4:5], s[14:15], 0, v[154:155]
	v_cvt_pk_bf16_f32 v1, v6, v7
	v_cvt_pk_bf16_f32 v2, v8, v9
	v_cvt_pk_bf16_f32 v3, v10, v11
	v_lshl_add_u64 v[4:5], v[4:5], 0, v[136:137]
	s_mov_b64 s[14:15], -1
	global_store_dwordx4 v[4:5], v[0:3], off nt
	s_cbranch_vccnz .LBB0_169
	s_andn2_b64 vcc, exec, s[0:1]
	s_cbranch_vccnz .LBB0_168
	s_barrier
	s_branch .LBB0_168

.LBB0_340:
	v_lshl_add_u32 v146, s30, 8, v148
	v_ashrrev_i32_e32 v147, 31, v146
	v_lshl_add_u64 v[154:155], v[146:147], 2, s[6:7]
	global_load_dword v147, v[154:155], off
	global_load_dword v229, v[154:155], off offset:64
	global_load_dword v230, v[154:155], off offset:128
	global_load_dword v231, v[154:155], off offset:192
	global_load_dword v232, v[154:155], off offset:512
	global_load_dword v233, v[154:155], off offset:576
	global_load_dword v234, v[154:155], off offset:640
	global_load_dword v235, v[154:155], off offset:704
	s_lshl_b32 s30, s31, 8
	s_ashr_i32 s31, s30, 31
	s_lshl_b64 s[30:31], s[30:31], 1
	s_waitcnt vmcnt(0)
	v_fmamk_f32 v147, v147, 0x3a800000, v153
	v_cmp_gt_f32_e32 vcc, s60, v147
	v_mul_f32_e32 v154, 0x4b800000, v147
	s_nop 0
	v_cndmask_b32_e32 v147, v147, v154, vcc
	v_rsq_f32_e32 v147, v147
	s_nop 0
	v_mul_f32_e32 v154, 0x45800000, v147
	v_cndmask_b32_e32 v154, v147, v154, vcc
	v_pk_mul_f32 v[124:125], v[124:125], v[154:155] op_sel_hi:[1,0]
	v_pk_mul_f32 v[120:121], v[120:121], v[154:155] op_sel_hi:[1,0]
	v_pk_mul_f32 v[126:127], v[126:127], v[154:155] op_sel_hi:[1,0]
	v_pk_mul_f32 v[156:157], v[122:123], v[154:155] op_sel_hi:[1,0]
	v_cvt_pk_bf16_f32 v122, v124, v125
	v_cvt_pk_bf16_f32 v124, v120, v121
	v_mov_b64_e32 v[120:121], s[80:81]
	v_cvt_pk_bf16_f32 v123, v126, v127
	v_mad_i64_i32 v[126:127], s[34:35], v146, s61, v[120:121]
	v_lshl_add_u64 v[126:127], v[126:127], 0, s[30:31]
	v_lshl_add_u64 v[126:127], v[126:127], 0, s[0:1]
	v_cvt_pk_bf16_f32 v125, v156, v157
	v_lshl_add_u64 v[126:127], v[126:127], 0, v[136:137]
	global_store_dwordx4 v[126:127], v[122:125], off nt
	v_pk_mul_f32 v[118:119], v[118:119], v[154:155] op_sel_hi:[1,0]
	v_pk_mul_f32 v[116:117], v[116:117], v[154:155] op_sel_hi:[1,0]
	v_pk_mul_f32 v[122:123], v[114:115], v[154:155] op_sel_hi:[1,0]
	v_pk_mul_f32 v[114:115], v[112:113], v[154:155] op_sel_hi:[1,0]
	v_cvt_pk_bf16_f32 v112, v116, v117
	v_cvt_pk_bf16_f32 v113, v118, v119
	v_cvt_pk_bf16_f32 v114, v114, v115
	v_cvt_pk_bf16_f32 v115, v122, v123
	global_store_dwordx4 v[126:127], v[112:115], off offset:256 nt
	s_nop 1
	v_or_b32_e32 v112, 16, v146
	v_ashrrev_i32_e32 v113, 31, v112
	v_lshl_add_u64 v[114:115], v[112:113], 2, s[6:7]
	s_nop 1
	v_fmamk_f32 v113, v229, 0x3a800000, v153
	v_cmp_gt_f32_e32 vcc, s60, v113
	v_mul_f32_e32 v114, 0x4b800000, v113
	s_nop 0
	v_cndmask_b32_e32 v113, v113, v114, vcc
	v_rsq_f32_e32 v113, v113
	s_nop 0
	v_mul_f32_e32 v114, 0x45800000, v113
	v_cndmask_b32_e32 v114, v113, v114, vcc
	v_pk_mul_f32 v[108:109], v[108:109], v[114:115] op_sel_hi:[1,0]
	v_pk_mul_f32 v[116:117], v[106:107], v[114:115] op_sel_hi:[1,0]
	v_pk_mul_f32 v[106:107], v[104:105], v[114:115] op_sel_hi:[1,0]
	v_cvt_pk_bf16_f32 v104, v108, v109
	v_mad_i64_i32 v[108:109], s[34:35], v112, s61, v[120:121]
	v_lshl_add_u64 v[108:109], v[108:109], 0, s[30:31]
	v_pk_mul_f32 v[110:111], v[110:111], v[114:115] op_sel_hi:[1,0]
	v_lshl_add_u64 v[108:109], v[108:109], 0, s[0:1]
	v_cvt_pk_bf16_f32 v105, v110, v111
	v_cvt_pk_bf16_f32 v106, v106, v107
	v_cvt_pk_bf16_f32 v107, v116, v117
	v_lshl_add_u64 v[108:109], v[108:109], 0, v[136:137]
	global_store_dwordx4 v[108:109], v[104:107], off nt
	v_pk_mul_f32 v[102:103], v[102:103], v[114:115] op_sel_hi:[1,0]
	v_pk_mul_f32 v[100:101], v[100:101], v[114:115] op_sel_hi:[1,0]
	v_pk_mul_f32 v[104:105], v[98:99], v[114:115] op_sel_hi:[1,0]
	v_pk_mul_f32 v[98:99], v[96:97], v[114:115] op_sel_hi:[1,0]
	v_cvt_pk_bf16_f32 v96, v100, v101
	v_cvt_pk_bf16_f32 v97, v102, v103
	v_cvt_pk_bf16_f32 v98, v98, v99
	v_cvt_pk_bf16_f32 v99, v104, v105
	global_store_dwordx4 v[108:109], v[96:99], off offset:256 nt
	s_nop 1
	v_or_b32_e32 v96, 32, v146
	v_ashrrev_i32_e32 v97, 31, v96
	v_lshl_add_u64 v[98:99], v[96:97], 2, s[6:7]
	s_nop 1
	v_fmamk_f32 v97, v230, 0x3a800000, v153
	v_cmp_gt_f32_e32 vcc, s60, v97
	v_mul_f32_e32 v98, 0x4b800000, v97
	s_nop 0
	v_cndmask_b32_e32 v97, v97, v98, vcc
	v_rsq_f32_e32 v97, v97
	s_nop 0
	v_mul_f32_e32 v98, 0x45800000, v97
	v_cndmask_b32_e32 v98, v97, v98, vcc
	v_pk_mul_f32 v[92:93], v[92:93], v[98:99] op_sel_hi:[1,0]
	v_pk_mul_f32 v[100:101], v[90:91], v[98:99] op_sel_hi:[1,0]
	v_pk_mul_f32 v[90:91], v[88:89], v[98:99] op_sel_hi:[1,0]
	v_cvt_pk_bf16_f32 v88, v92, v93
	v_mad_i64_i32 v[92:93], s[34:35], v96, s61, v[120:121]
	v_lshl_add_u64 v[92:93], v[92:93], 0, s[30:31]
	v_pk_mul_f32 v[94:95], v[94:95], v[98:99] op_sel_hi:[1,0]
	v_lshl_add_u64 v[92:93], v[92:93], 0, s[0:1]
	v_cvt_pk_bf16_f32 v89, v94, v95
	v_cvt_pk_bf16_f32 v90, v90, v91
	v_cvt_pk_bf16_f32 v91, v100, v101
	v_lshl_add_u64 v[92:93], v[92:93], 0, v[136:137]
	global_store_dwordx4 v[92:93], v[88:91], off nt
	v_pk_mul_f32 v[86:87], v[86:87], v[98:99] op_sel_hi:[1,0]
	v_pk_mul_f32 v[84:85], v[84:85], v[98:99] op_sel_hi:[1,0]
	v_pk_mul_f32 v[88:89], v[82:83], v[98:99] op_sel_hi:[1,0]
	v_pk_mul_f32 v[82:83], v[80:81], v[98:99] op_sel_hi:[1,0]
	v_cvt_pk_bf16_f32 v80, v84, v85
	v_cvt_pk_bf16_f32 v81, v86, v87
	v_cvt_pk_bf16_f32 v82, v82, v83
	v_cvt_pk_bf16_f32 v83, v88, v89
	global_store_dwordx4 v[92:93], v[80:83], off offset:256 nt
	s_nop 1
	v_or_b32_e32 v80, 48, v146
	v_ashrrev_i32_e32 v81, 31, v80
	v_lshl_add_u64 v[82:83], v[80:81], 2, s[6:7]
	s_nop 1
	v_fmamk_f32 v81, v231, 0x3a800000, v153
	v_cmp_gt_f32_e32 vcc, s60, v81
	v_mul_f32_e32 v82, 0x4b800000, v81
	s_nop 0
	v_cndmask_b32_e32 v81, v81, v82, vcc
	v_rsq_f32_e32 v81, v81
	s_nop 0
	v_mul_f32_e32 v82, 0x45800000, v81
	v_cndmask_b32_e32 v82, v81, v82, vcc
	v_pk_mul_f32 v[76:77], v[76:77], v[82:83] op_sel_hi:[1,0]
	v_pk_mul_f32 v[84:85], v[74:75], v[82:83] op_sel_hi:[1,0]
	v_pk_mul_f32 v[74:75], v[72:73], v[82:83] op_sel_hi:[1,0]
	v_cvt_pk_bf16_f32 v72, v76, v77
	v_mad_i64_i32 v[76:77], s[34:35], v80, s61, v[120:121]
	v_lshl_add_u64 v[76:77], v[76:77], 0, s[30:31]
	v_pk_mul_f32 v[78:79], v[78:79], v[82:83] op_sel_hi:[1,0]
	v_lshl_add_u64 v[76:77], v[76:77], 0, s[0:1]
	v_cvt_pk_bf16_f32 v73, v78, v79
	v_cvt_pk_bf16_f32 v74, v74, v75
	v_cvt_pk_bf16_f32 v75, v84, v85
	v_lshl_add_u64 v[76:77], v[76:77], 0, v[136:137]
	global_store_dwordx4 v[76:77], v[72:75], off nt
	v_pk_mul_f32 v[70:71], v[70:71], v[82:83] op_sel_hi:[1,0]
	v_pk_mul_f32 v[68:69], v[68:69], v[82:83] op_sel_hi:[1,0]
	v_pk_mul_f32 v[72:73], v[66:67], v[82:83] op_sel_hi:[1,0]
	v_pk_mul_f32 v[66:67], v[64:65], v[82:83] op_sel_hi:[1,0]
	v_cvt_pk_bf16_f32 v64, v68, v69
	v_cvt_pk_bf16_f32 v65, v70, v71
	v_cvt_pk_bf16_f32 v66, v66, v67
	v_cvt_pk_bf16_f32 v67, v72, v73
	global_store_dwordx4 v[76:77], v[64:67], off offset:256 nt
	s_nop 1
	v_add_u32_e32 v64, 0x80, v146
	v_ashrrev_i32_e32 v65, 31, v64
	v_lshl_add_u64 v[66:67], v[64:65], 2, s[6:7]
	s_nop 1
	v_fmamk_f32 v65, v232, 0x3a800000, v153
	v_cmp_gt_f32_e32 vcc, s60, v65
	v_mul_f32_e32 v66, 0x4b800000, v65
	s_nop 0
	v_cndmask_b32_e32 v65, v65, v66, vcc
	v_rsq_f32_e32 v65, v65
	s_nop 0
	v_mul_f32_e32 v66, 0x45800000, v65
	v_cndmask_b32_e32 v66, v65, v66, vcc
	v_pk_mul_f32 v[60:61], v[60:61], v[66:67] op_sel_hi:[1,0]
	v_pk_mul_f32 v[68:69], v[58:59], v[66:67] op_sel_hi:[1,0]
	v_pk_mul_f32 v[58:59], v[56:57], v[66:67] op_sel_hi:[1,0]
	v_cvt_pk_bf16_f32 v56, v60, v61
	v_mad_i64_i32 v[60:61], s[34:35], v64, s61, v[120:121]
	v_lshl_add_u64 v[60:61], v[60:61], 0, s[30:31]
	v_pk_mul_f32 v[62:63], v[62:63], v[66:67] op_sel_hi:[1,0]
	v_lshl_add_u64 v[60:61], v[60:61], 0, s[0:1]
	v_cvt_pk_bf16_f32 v57, v62, v63
	v_cvt_pk_bf16_f32 v58, v58, v59
	v_cvt_pk_bf16_f32 v59, v68, v69
	v_lshl_add_u64 v[60:61], v[60:61], 0, v[136:137]
	global_store_dwordx4 v[60:61], v[56:59], off nt
	v_pk_mul_f32 v[54:55], v[54:55], v[66:67] op_sel_hi:[1,0]
	v_pk_mul_f32 v[52:53], v[52:53], v[66:67] op_sel_hi:[1,0]
	v_pk_mul_f32 v[56:57], v[50:51], v[66:67] op_sel_hi:[1,0]
	v_pk_mul_f32 v[50:51], v[48:49], v[66:67] op_sel_hi:[1,0]
	v_cvt_pk_bf16_f32 v48, v52, v53
	v_cvt_pk_bf16_f32 v49, v54, v55
	v_cvt_pk_bf16_f32 v50, v50, v51
	v_cvt_pk_bf16_f32 v51, v56, v57
	global_store_dwordx4 v[60:61], v[48:51], off offset:256 nt
	s_nop 1
	v_add_u32_e32 v48, 0x90, v146
	v_ashrrev_i32_e32 v49, 31, v48
	v_lshl_add_u64 v[50:51], v[48:49], 2, s[6:7]
	s_nop 1
	v_fmamk_f32 v49, v233, 0x3a800000, v153
	v_cmp_gt_f32_e32 vcc, s60, v49
	v_mul_f32_e32 v50, 0x4b800000, v49
	s_nop 0
	v_cndmask_b32_e32 v49, v49, v50, vcc
	v_rsq_f32_e32 v49, v49
	s_nop 0
	v_mul_f32_e32 v50, 0x45800000, v49
	v_cndmask_b32_e32 v50, v49, v50, vcc
	v_pk_mul_f32 v[44:45], v[44:45], v[50:51] op_sel_hi:[1,0]
	v_pk_mul_f32 v[52:53], v[42:43], v[50:51] op_sel_hi:[1,0]
	v_pk_mul_f32 v[42:43], v[40:41], v[50:51] op_sel_hi:[1,0]
	v_cvt_pk_bf16_f32 v40, v44, v45
	v_mad_i64_i32 v[44:45], s[34:35], v48, s61, v[120:121]
	v_lshl_add_u64 v[44:45], v[44:45], 0, s[30:31]
	v_pk_mul_f32 v[46:47], v[46:47], v[50:51] op_sel_hi:[1,0]
	v_lshl_add_u64 v[44:45], v[44:45], 0, s[0:1]
	v_cvt_pk_bf16_f32 v41, v46, v47
	v_cvt_pk_bf16_f32 v42, v42, v43
	v_cvt_pk_bf16_f32 v43, v52, v53
	v_lshl_add_u64 v[44:45], v[44:45], 0, v[136:137]
	global_store_dwordx4 v[44:45], v[40:43], off nt
	v_pk_mul_f32 v[38:39], v[38:39], v[50:51] op_sel_hi:[1,0]
	v_pk_mul_f32 v[36:37], v[36:37], v[50:51] op_sel_hi:[1,0]
	v_pk_mul_f32 v[40:41], v[34:35], v[50:51] op_sel_hi:[1,0]
	v_pk_mul_f32 v[34:35], v[32:33], v[50:51] op_sel_hi:[1,0]
	v_cvt_pk_bf16_f32 v32, v36, v37
	v_cvt_pk_bf16_f32 v33, v38, v39
	v_cvt_pk_bf16_f32 v34, v34, v35
	v_cvt_pk_bf16_f32 v35, v40, v41
	global_store_dwordx4 v[44:45], v[32:35], off offset:256 nt
	s_nop 1
	v_add_u32_e32 v32, 0xa0, v146
	v_ashrrev_i32_e32 v33, 31, v32
	v_lshl_add_u64 v[34:35], v[32:33], 2, s[6:7]
	s_nop 1
	v_fmamk_f32 v33, v234, 0x3a800000, v153
	v_cmp_gt_f32_e32 vcc, s60, v33
	v_mul_f32_e32 v34, 0x4b800000, v33
	s_nop 0
	v_cndmask_b32_e32 v33, v33, v34, vcc
	v_rsq_f32_e32 v33, v33
	s_nop 0
	v_mul_f32_e32 v34, 0x45800000, v33
	v_cndmask_b32_e32 v34, v33, v34, vcc
	v_pk_mul_f32 v[28:29], v[28:29], v[34:35] op_sel_hi:[1,0]
	v_pk_mul_f32 v[36:37], v[26:27], v[34:35] op_sel_hi:[1,0]
	v_pk_mul_f32 v[26:27], v[24:25], v[34:35] op_sel_hi:[1,0]
	v_cvt_pk_bf16_f32 v24, v28, v29
	v_mad_i64_i32 v[28:29], s[34:35], v32, s61, v[120:121]
	v_lshl_add_u64 v[28:29], v[28:29], 0, s[30:31]
	v_pk_mul_f32 v[30:31], v[30:31], v[34:35] op_sel_hi:[1,0]
	v_lshl_add_u64 v[28:29], v[28:29], 0, s[0:1]
	v_cvt_pk_bf16_f32 v25, v30, v31
	v_cvt_pk_bf16_f32 v26, v26, v27
	v_cvt_pk_bf16_f32 v27, v36, v37
	v_lshl_add_u64 v[28:29], v[28:29], 0, v[136:137]
	global_store_dwordx4 v[28:29], v[24:27], off nt
	v_pk_mul_f32 v[22:23], v[22:23], v[34:35] op_sel_hi:[1,0]
	v_pk_mul_f32 v[20:21], v[20:21], v[34:35] op_sel_hi:[1,0]
	v_pk_mul_f32 v[24:25], v[18:19], v[34:35] op_sel_hi:[1,0]
	v_pk_mul_f32 v[18:19], v[16:17], v[34:35] op_sel_hi:[1,0]
	v_cvt_pk_bf16_f32 v16, v20, v21
	v_cvt_pk_bf16_f32 v17, v22, v23
	v_cvt_pk_bf16_f32 v18, v18, v19
	v_cvt_pk_bf16_f32 v19, v24, v25
	global_store_dwordx4 v[28:29], v[16:19], off offset:256 nt
	s_nop 1
	v_add_u32_e32 v16, 0xb0, v146
	v_ashrrev_i32_e32 v17, 31, v16
	v_lshl_add_u64 v[18:19], v[16:17], 2, s[6:7]
	s_nop 1
	v_fmamk_f32 v17, v235, 0x3a800000, v153
	v_cmp_gt_f32_e32 vcc, s60, v17
	v_mul_f32_e32 v18, 0x4b800000, v17
	s_nop 0
	v_cndmask_b32_e32 v17, v17, v18, vcc
	v_rsq_f32_e32 v17, v17
	s_nop 0
	v_mul_f32_e32 v18, 0x45800000, v17
	v_cndmask_b32_e32 v18, v17, v18, vcc
	v_pk_mul_f32 v[12:13], v[12:13], v[18:19] op_sel_hi:[1,0]
	v_pk_mul_f32 v[20:21], v[10:11], v[18:19] op_sel_hi:[1,0]
	v_pk_mul_f32 v[10:11], v[8:9], v[18:19] op_sel_hi:[1,0]
	v_cvt_pk_bf16_f32 v8, v12, v13
	v_mad_i64_i32 v[12:13], s[34:35], v16, s61, v[120:121]
	v_lshl_add_u64 v[12:13], v[12:13], 0, s[30:31]
	v_pk_mul_f32 v[14:15], v[14:15], v[18:19] op_sel_hi:[1,0]
	v_lshl_add_u64 v[12:13], v[12:13], 0, s[0:1]
	v_cvt_pk_bf16_f32 v9, v14, v15
	v_cvt_pk_bf16_f32 v10, v10, v11
	v_cvt_pk_bf16_f32 v11, v20, v21
	v_lshl_add_u64 v[12:13], v[12:13], 0, v[136:137]
	global_store_dwordx4 v[12:13], v[8:11], off nt
	v_pk_mul_f32 v[6:7], v[6:7], v[18:19] op_sel_hi:[1,0]
	v_pk_mul_f32 v[4:5], v[4:5], v[18:19] op_sel_hi:[1,0]
	v_pk_mul_f32 v[8:9], v[2:3], v[18:19] op_sel_hi:[1,0]
	v_pk_mul_f32 v[2:3], v[0:1], v[18:19] op_sel_hi:[1,0]
	v_cvt_pk_bf16_f32 v0, v4, v5
	v_cvt_pk_bf16_f32 v1, v6, v7
	v_cvt_pk_bf16_f32 v2, v2, v3
	v_cvt_pk_bf16_f32 v3, v8, v9
	s_mov_b64 s[30:31], -1
	s_andn2_b64 vcc, exec, s[2:3]
	global_store_dwordx4 v[12:13], v[0:3], off offset:256 nt
	s_cbranch_vccnz .LBB0_333
	s_andn2_b64 vcc, exec, s[4:5]
	s_cbranch_vccnz .LBB0_332
	s_barrier
	s_branch .LBB0_332

.LBB0_1630:
	v_lshl_add_u32 v164, s4, 8, v138
	v_ashrrev_i32_e32 v165, 31, v164
	v_lshl_add_u64 v[166:167], v[164:165], 2, s[6:7]
	global_load_dword v165, v[166:167], off
	global_load_dword v189, v[166:167], off offset:64
	global_load_dword v190, v[166:167], off offset:128
	global_load_dword v191, v[166:167], off offset:192
	global_load_dword v192, v[166:167], off offset:512
	global_load_dword v193, v[166:167], off offset:576
	global_load_dword v194, v[166:167], off offset:640
	global_load_dword v195, v[166:167], off offset:704
	s_lshl_b32 s5, s5, 1
	s_mul_i32 s4, s4, 44
	s_add_i32 s4, s4, s5
	s_or_b32 s4, s4, s35
	s_ashr_i32 s5, s4, 31
	s_lshl_b64 s[4:5], s[4:5], 15
	s_add_u32 s18, s80, s4
	s_addc_u32 s19, s81, s5
	s_waitcnt vmcnt(0)
	v_fmamk_f32 v165, v165, 0x3a800000, v171
	v_mul_f32_e32 v172, 0x4b800000, v165
	v_cmp_gt_f32_e32 vcc, s40, v165
	s_nop 1
	v_cndmask_b32_e32 v165, v165, v172, vcc
	v_rsq_f32_e32 v165, v165
	v_lshl_add_u64 v[172:173], s[18:19], 0, v[140:141]
	v_lshl_add_u64 v[172:173], v[172:173], 0, v[136:137]
	v_mul_f32_e32 v174, 0x45800000, v165
	v_cndmask_b32_e32 v174, v165, v174, vcc
	v_pk_mul_f32 v[124:125], v[124:125], v[174:175] op_sel_hi:[1,0]
	v_pk_mul_f32 v[126:127], v[126:127], v[174:175] op_sel_hi:[1,0]
	v_pk_mul_f32 v[120:121], v[120:121], v[174:175] op_sel_hi:[1,0]
	v_pk_mul_f32 v[122:123], v[122:123], v[174:175] op_sel_hi:[1,0]
	v_pk_mul_f32 v[116:117], v[116:117], v[174:175] op_sel_hi:[1,0]
	v_pk_mul_f32 v[118:119], v[118:119], v[174:175] op_sel_hi:[1,0]
	v_pk_mul_f32 v[112:113], v[112:113], v[174:175] op_sel_hi:[1,0]
	v_pk_mul_f32 v[114:115], v[114:115], v[174:175] op_sel_hi:[1,0]
	v_mul_f32_e32 v165, 0xbfb8aa3b, v124
	v_mul_f32_e32 v174, 0xbfb8aa3b, v125
	v_mul_f32_e32 v175, 0xbfb8aa3b, v126
	v_mul_f32_e32 v176, 0xbfb8aa3b, v127
	v_mul_f32_e32 v177, 0xbfb8aa3b, v120
	v_mul_f32_e32 v178, 0xbfb8aa3b, v121
	v_mul_f32_e32 v179, 0xbfb8aa3b, v122
	v_mul_f32_e32 v180, 0xbfb8aa3b, v123
	v_exp_f32_e32 v165, v165
	v_exp_f32_e32 v174, v174
	v_exp_f32_e32 v175, v175
	v_exp_f32_e32 v176, v176
	v_exp_f32_e32 v177, v177
	v_exp_f32_e32 v178, v178
	v_exp_f32_e32 v179, v179
	v_exp_f32_e32 v180, v180
	v_add_f32_e32 v165, 1.0, v165
	v_add_f32_e32 v181, 1.0, v174
	v_add_f32_e32 v182, 1.0, v175
	v_add_f32_e32 v183, 1.0, v176
	v_add_f32_e32 v184, 1.0, v177
	v_add_f32_e32 v185, 1.0, v178
	v_add_f32_e32 v186, 1.0, v179
	v_add_f32_e32 v187, 1.0, v180
	v_rcp_f32_e32 v174, v165
	v_rcp_f32_e32 v175, v181
	v_rcp_f32_e32 v176, v182
	v_rcp_f32_e32 v177, v183
	v_rcp_f32_e32 v178, v184
	v_rcp_f32_e32 v179, v185
	v_rcp_f32_e32 v180, v186
	v_rcp_f32_e32 v181, v187
	v_pk_mul_f32 v[124:125], v[124:125], v[174:175]
	v_pk_mul_f32 v[126:127], v[126:127], v[176:177]
	v_pk_mul_f32 v[120:121], v[120:121], v[178:179]
	v_pk_mul_f32 v[122:123], v[122:123], v[180:181]
	v_pk_mul_f32 v[116:117], v[116:117], v[124:125]
	v_pk_mul_f32 v[118:119], v[118:119], v[126:127]
	v_pk_mul_f32 v[120:121], v[112:113], v[120:121]
	v_pk_mul_f32 v[122:123], v[114:115], v[122:123]
	v_cvt_pk_bf16_f32 v112, v116, v117
	v_cvt_pk_bf16_f32 v113, v118, v119
	v_cvt_pk_bf16_f32 v114, v120, v121
	v_cvt_pk_bf16_f32 v115, v122, v123
	global_store_dwordx4 v[172:173], v[112:115], off nt
	s_nop 1
	v_fmamk_f32 v112, v189, 0x3a800000, v171
	v_mul_f32_e32 v113, 0x4b800000, v112
	v_cmp_gt_f32_e32 vcc, s40, v112
	s_nop 1
	v_cndmask_b32_e32 v112, v112, v113, vcc
	v_rsq_f32_e32 v114, v112
	v_lshl_add_u64 v[112:113], s[18:19], 0, v[142:143]
	v_lshl_add_u64 v[112:113], v[112:113], 0, v[136:137]
	v_mul_f32_e32 v115, 0x45800000, v114
	v_cndmask_b32_e32 v114, v114, v115, vcc
	v_pk_mul_f32 v[108:109], v[108:109], v[114:115] op_sel_hi:[1,0]
	v_pk_mul_f32 v[110:111], v[110:111], v[114:115] op_sel_hi:[1,0]
	v_pk_mul_f32 v[104:105], v[104:105], v[114:115] op_sel_hi:[1,0]
	v_pk_mul_f32 v[106:107], v[106:107], v[114:115] op_sel_hi:[1,0]
	v_pk_mul_f32 v[100:101], v[100:101], v[114:115] op_sel_hi:[1,0]
	v_pk_mul_f32 v[102:103], v[102:103], v[114:115] op_sel_hi:[1,0]
	v_pk_mul_f32 v[96:97], v[96:97], v[114:115] op_sel_hi:[1,0]
	v_pk_mul_f32 v[98:99], v[98:99], v[114:115] op_sel_hi:[1,0]
	v_mul_f32_e32 v114, 0xbfb8aa3b, v108
	v_mul_f32_e32 v115, 0xbfb8aa3b, v109
	v_mul_f32_e32 v116, 0xbfb8aa3b, v110
	v_mul_f32_e32 v117, 0xbfb8aa3b, v111
	v_mul_f32_e32 v118, 0xbfb8aa3b, v104
	v_mul_f32_e32 v119, 0xbfb8aa3b, v105
	v_mul_f32_e32 v120, 0xbfb8aa3b, v106
	v_mul_f32_e32 v121, 0xbfb8aa3b, v107
	v_exp_f32_e32 v114, v114
	v_exp_f32_e32 v115, v115
	v_exp_f32_e32 v116, v116
	v_exp_f32_e32 v117, v117
	v_exp_f32_e32 v118, v118
	v_exp_f32_e32 v119, v119
	v_exp_f32_e32 v120, v120
	v_exp_f32_e32 v121, v121
	v_add_f32_e32 v114, 1.0, v114
	v_add_f32_e32 v115, 1.0, v115
	v_add_f32_e32 v116, 1.0, v116
	v_add_f32_e32 v117, 1.0, v117
	v_add_f32_e32 v118, 1.0, v118
	v_add_f32_e32 v119, 1.0, v119
	v_add_f32_e32 v120, 1.0, v120
	v_add_f32_e32 v121, 1.0, v121
	v_rcp_f32_e32 v114, v114
	v_rcp_f32_e32 v115, v115
	v_rcp_f32_e32 v116, v116
	v_rcp_f32_e32 v117, v117
	v_rcp_f32_e32 v118, v118
	v_rcp_f32_e32 v119, v119
	v_rcp_f32_e32 v120, v120
	v_rcp_f32_e32 v121, v121
	v_pk_mul_f32 v[108:109], v[108:109], v[114:115]
	v_pk_mul_f32 v[110:111], v[110:111], v[116:117]
	v_pk_mul_f32 v[104:105], v[104:105], v[118:119]
	v_pk_mul_f32 v[106:107], v[106:107], v[120:121]
	v_pk_mul_f32 v[100:101], v[100:101], v[108:109]
	v_pk_mul_f32 v[102:103], v[102:103], v[110:111]
	v_pk_mul_f32 v[104:105], v[96:97], v[104:105]
	v_pk_mul_f32 v[106:107], v[98:99], v[106:107]
	v_cvt_pk_bf16_f32 v96, v100, v101
	v_cvt_pk_bf16_f32 v97, v102, v103
	v_cvt_pk_bf16_f32 v98, v104, v105
	v_cvt_pk_bf16_f32 v99, v106, v107
	global_store_dwordx4 v[112:113], v[96:99], off nt
	s_nop 1
	v_fmamk_f32 v96, v190, 0x3a800000, v171
	v_mul_f32_e32 v97, 0x4b800000, v96
	v_cmp_gt_f32_e32 vcc, s40, v96
	s_nop 1
	v_cndmask_b32_e32 v96, v96, v97, vcc
	v_rsq_f32_e32 v98, v96
	v_lshl_add_u64 v[96:97], s[18:19], 0, v[144:145]
	v_lshl_add_u64 v[96:97], v[96:97], 0, v[136:137]
	v_mul_f32_e32 v99, 0x45800000, v98
	v_cndmask_b32_e32 v98, v98, v99, vcc
	v_pk_mul_f32 v[92:93], v[92:93], v[98:99] op_sel_hi:[1,0]
	v_pk_mul_f32 v[94:95], v[94:95], v[98:99] op_sel_hi:[1,0]
	v_pk_mul_f32 v[88:89], v[88:89], v[98:99] op_sel_hi:[1,0]
	v_pk_mul_f32 v[90:91], v[90:91], v[98:99] op_sel_hi:[1,0]
	v_pk_mul_f32 v[84:85], v[84:85], v[98:99] op_sel_hi:[1,0]
	v_pk_mul_f32 v[86:87], v[86:87], v[98:99] op_sel_hi:[1,0]
	v_pk_mul_f32 v[80:81], v[80:81], v[98:99] op_sel_hi:[1,0]
	v_pk_mul_f32 v[82:83], v[82:83], v[98:99] op_sel_hi:[1,0]
	v_mul_f32_e32 v98, 0xbfb8aa3b, v92
	v_mul_f32_e32 v99, 0xbfb8aa3b, v93
	v_mul_f32_e32 v100, 0xbfb8aa3b, v94
	v_mul_f32_e32 v101, 0xbfb8aa3b, v95
	v_mul_f32_e32 v102, 0xbfb8aa3b, v88
	v_mul_f32_e32 v103, 0xbfb8aa3b, v89
	v_mul_f32_e32 v104, 0xbfb8aa3b, v90
	v_mul_f32_e32 v105, 0xbfb8aa3b, v91
	v_exp_f32_e32 v98, v98
	v_exp_f32_e32 v99, v99
	v_exp_f32_e32 v100, v100
	v_exp_f32_e32 v101, v101
	v_exp_f32_e32 v102, v102
	v_exp_f32_e32 v103, v103
	v_exp_f32_e32 v104, v104
	v_exp_f32_e32 v105, v105
	v_add_f32_e32 v98, 1.0, v98
	v_add_f32_e32 v99, 1.0, v99
	v_add_f32_e32 v100, 1.0, v100
	v_add_f32_e32 v101, 1.0, v101
	v_add_f32_e32 v102, 1.0, v102
	v_add_f32_e32 v103, 1.0, v103
	v_add_f32_e32 v104, 1.0, v104
	v_add_f32_e32 v105, 1.0, v105
	v_rcp_f32_e32 v98, v98
	v_rcp_f32_e32 v99, v99
	v_rcp_f32_e32 v100, v100
	v_rcp_f32_e32 v101, v101
	v_rcp_f32_e32 v102, v102
	v_rcp_f32_e32 v103, v103
	v_rcp_f32_e32 v104, v104
	v_rcp_f32_e32 v105, v105
	v_pk_mul_f32 v[92:93], v[92:93], v[98:99]
	v_pk_mul_f32 v[94:95], v[94:95], v[100:101]
	v_pk_mul_f32 v[88:89], v[88:89], v[102:103]
	v_pk_mul_f32 v[90:91], v[90:91], v[104:105]
	v_pk_mul_f32 v[84:85], v[84:85], v[92:93]
	v_pk_mul_f32 v[86:87], v[86:87], v[94:95]
	v_pk_mul_f32 v[88:89], v[80:81], v[88:89]
	v_pk_mul_f32 v[90:91], v[82:83], v[90:91]
	v_cvt_pk_bf16_f32 v80, v84, v85
	v_cvt_pk_bf16_f32 v81, v86, v87
	v_cvt_pk_bf16_f32 v82, v88, v89
	v_cvt_pk_bf16_f32 v83, v90, v91
	global_store_dwordx4 v[96:97], v[80:83], off nt
	s_nop 1
	s_nop 0
	v_add_u32_e32 v80, 0x80, v164
	v_ashrrev_i32_e32 v81, 31, v80
	v_lshl_add_u64 v[80:81], v[80:81], 2, s[6:7]
	v_fmamk_f32 v82, v191, 0x3a800000, v171
	v_mul_f32_e32 v83, 0x4b800000, v82
	v_cmp_gt_f32_e32 vcc, s40, v82
	s_nop 1
	v_cndmask_b32_e32 v82, v82, v83, vcc
	v_rsq_f32_e32 v84, v82
	v_lshl_add_u64 v[82:83], s[18:19], 0, v[146:147]
	v_lshl_add_u64 v[82:83], v[82:83], 0, v[136:137]
	v_mul_f32_e32 v85, 0x45800000, v84
	v_cndmask_b32_e32 v84, v84, v85, vcc
	v_pk_mul_f32 v[76:77], v[76:77], v[84:85] op_sel_hi:[1,0]
	v_pk_mul_f32 v[78:79], v[78:79], v[84:85] op_sel_hi:[1,0]
	v_pk_mul_f32 v[72:73], v[72:73], v[84:85] op_sel_hi:[1,0]
	v_pk_mul_f32 v[74:75], v[74:75], v[84:85] op_sel_hi:[1,0]
	v_pk_mul_f32 v[68:69], v[68:69], v[84:85] op_sel_hi:[1,0]
	v_pk_mul_f32 v[70:71], v[70:71], v[84:85] op_sel_hi:[1,0]
	v_pk_mul_f32 v[64:65], v[64:65], v[84:85] op_sel_hi:[1,0]
	v_pk_mul_f32 v[66:67], v[66:67], v[84:85] op_sel_hi:[1,0]
	v_mul_f32_e32 v84, 0xbfb8aa3b, v76
	v_mul_f32_e32 v85, 0xbfb8aa3b, v77
	v_mul_f32_e32 v86, 0xbfb8aa3b, v78
	v_mul_f32_e32 v87, 0xbfb8aa3b, v79
	v_mul_f32_e32 v88, 0xbfb8aa3b, v72
	v_mul_f32_e32 v89, 0xbfb8aa3b, v73
	v_mul_f32_e32 v90, 0xbfb8aa3b, v74
	v_mul_f32_e32 v91, 0xbfb8aa3b, v75
	v_exp_f32_e32 v84, v84
	v_exp_f32_e32 v85, v85
	v_exp_f32_e32 v86, v86
	v_exp_f32_e32 v87, v87
	v_exp_f32_e32 v88, v88
	v_exp_f32_e32 v89, v89
	v_exp_f32_e32 v90, v90
	v_exp_f32_e32 v91, v91
	v_add_f32_e32 v84, 1.0, v84
	v_add_f32_e32 v85, 1.0, v85
	v_add_f32_e32 v86, 1.0, v86
	v_add_f32_e32 v87, 1.0, v87
	v_add_f32_e32 v88, 1.0, v88
	v_add_f32_e32 v89, 1.0, v89
	v_add_f32_e32 v90, 1.0, v90
	v_add_f32_e32 v91, 1.0, v91
	v_rcp_f32_e32 v84, v84
	v_rcp_f32_e32 v85, v85
	v_rcp_f32_e32 v86, v86
	v_rcp_f32_e32 v87, v87
	v_rcp_f32_e32 v88, v88
	v_rcp_f32_e32 v89, v89
	v_rcp_f32_e32 v90, v90
	v_rcp_f32_e32 v91, v91
	v_pk_mul_f32 v[76:77], v[76:77], v[84:85]
	v_pk_mul_f32 v[78:79], v[78:79], v[86:87]
	v_pk_mul_f32 v[72:73], v[72:73], v[88:89]
	v_pk_mul_f32 v[74:75], v[74:75], v[90:91]
	v_pk_mul_f32 v[68:69], v[68:69], v[76:77]
	v_pk_mul_f32 v[70:71], v[70:71], v[78:79]
	v_pk_mul_f32 v[72:73], v[64:65], v[72:73]
	v_pk_mul_f32 v[74:75], v[66:67], v[74:75]
	v_cvt_pk_bf16_f32 v64, v68, v69
	v_cvt_pk_bf16_f32 v65, v70, v71
	v_cvt_pk_bf16_f32 v66, v72, v73
	v_cvt_pk_bf16_f32 v67, v74, v75
	global_store_dwordx4 v[82:83], v[64:67], off nt
	s_nop 1
	s_nop 0
	v_add_u32_e32 v64, 0x90, v164
	v_ashrrev_i32_e32 v65, 31, v64
	v_lshl_add_u64 v[64:65], v[64:65], 2, s[6:7]
	v_fmamk_f32 v66, v192, 0x3a800000, v171
	v_mul_f32_e32 v67, 0x4b800000, v66
	v_cmp_gt_f32_e32 vcc, s40, v66
	s_nop 1
	v_cndmask_b32_e32 v66, v66, v67, vcc
	v_rsq_f32_e32 v68, v66
	v_lshl_add_u64 v[66:67], s[18:19], 0, v[148:149]
	v_lshl_add_u64 v[66:67], v[66:67], 0, v[136:137]
	v_mul_f32_e32 v69, 0x45800000, v68
	v_cndmask_b32_e32 v68, v68, v69, vcc
	v_pk_mul_f32 v[60:61], v[60:61], v[68:69] op_sel_hi:[1,0]
	v_pk_mul_f32 v[62:63], v[62:63], v[68:69] op_sel_hi:[1,0]
	v_pk_mul_f32 v[56:57], v[56:57], v[68:69] op_sel_hi:[1,0]
	v_pk_mul_f32 v[58:59], v[58:59], v[68:69] op_sel_hi:[1,0]
	v_pk_mul_f32 v[52:53], v[52:53], v[68:69] op_sel_hi:[1,0]
	v_pk_mul_f32 v[54:55], v[54:55], v[68:69] op_sel_hi:[1,0]
	v_pk_mul_f32 v[48:49], v[48:49], v[68:69] op_sel_hi:[1,0]
	v_pk_mul_f32 v[50:51], v[50:51], v[68:69] op_sel_hi:[1,0]
	v_mul_f32_e32 v68, 0xbfb8aa3b, v60
	v_mul_f32_e32 v69, 0xbfb8aa3b, v61
	v_mul_f32_e32 v70, 0xbfb8aa3b, v62
	v_mul_f32_e32 v71, 0xbfb8aa3b, v63
	v_mul_f32_e32 v72, 0xbfb8aa3b, v56
	v_mul_f32_e32 v73, 0xbfb8aa3b, v57
	v_mul_f32_e32 v74, 0xbfb8aa3b, v58
	v_mul_f32_e32 v75, 0xbfb8aa3b, v59
	v_exp_f32_e32 v68, v68
	v_exp_f32_e32 v69, v69
	v_exp_f32_e32 v70, v70
	v_exp_f32_e32 v71, v71
	v_exp_f32_e32 v72, v72
	v_exp_f32_e32 v73, v73
	v_exp_f32_e32 v74, v74
	v_exp_f32_e32 v75, v75
	v_add_f32_e32 v68, 1.0, v68
	v_add_f32_e32 v69, 1.0, v69
	v_add_f32_e32 v70, 1.0, v70
	v_add_f32_e32 v71, 1.0, v71
	v_add_f32_e32 v72, 1.0, v72
	v_add_f32_e32 v73, 1.0, v73
	v_add_f32_e32 v74, 1.0, v74
	v_add_f32_e32 v75, 1.0, v75
	v_rcp_f32_e32 v68, v68
	v_rcp_f32_e32 v69, v69
	v_rcp_f32_e32 v70, v70
	v_rcp_f32_e32 v71, v71
	v_rcp_f32_e32 v72, v72
	v_rcp_f32_e32 v73, v73
	v_rcp_f32_e32 v74, v74
	v_rcp_f32_e32 v75, v75
	v_pk_mul_f32 v[60:61], v[60:61], v[68:69]
	v_pk_mul_f32 v[62:63], v[62:63], v[70:71]
	v_pk_mul_f32 v[56:57], v[56:57], v[72:73]
	v_pk_mul_f32 v[58:59], v[58:59], v[74:75]
	v_pk_mul_f32 v[52:53], v[52:53], v[60:61]
	v_pk_mul_f32 v[54:55], v[54:55], v[62:63]
	v_pk_mul_f32 v[56:57], v[48:49], v[56:57]
	v_pk_mul_f32 v[58:59], v[50:51], v[58:59]
	v_cvt_pk_bf16_f32 v48, v52, v53
	v_cvt_pk_bf16_f32 v49, v54, v55
	v_cvt_pk_bf16_f32 v50, v56, v57
	v_cvt_pk_bf16_f32 v51, v58, v59
	global_store_dwordx4 v[66:67], v[48:51], off nt
	s_nop 1
	s_nop 0
	v_add_u32_e32 v48, 0xa0, v164
	v_ashrrev_i32_e32 v49, 31, v48
	v_lshl_add_u64 v[48:49], v[48:49], 2, s[6:7]
	v_fmamk_f32 v50, v193, 0x3a800000, v171
	v_mul_f32_e32 v51, 0x4b800000, v50
	v_cmp_gt_f32_e32 vcc, s40, v50
	s_nop 1
	v_cndmask_b32_e32 v50, v50, v51, vcc
	v_rsq_f32_e32 v52, v50
	v_lshl_add_u64 v[50:51], s[18:19], 0, v[150:151]
	v_lshl_add_u64 v[50:51], v[50:51], 0, v[136:137]
	v_mul_f32_e32 v53, 0x45800000, v52
	v_cndmask_b32_e32 v52, v52, v53, vcc
	v_pk_mul_f32 v[44:45], v[44:45], v[52:53] op_sel_hi:[1,0]
	v_pk_mul_f32 v[46:47], v[46:47], v[52:53] op_sel_hi:[1,0]
	v_pk_mul_f32 v[40:41], v[40:41], v[52:53] op_sel_hi:[1,0]
	v_pk_mul_f32 v[42:43], v[42:43], v[52:53] op_sel_hi:[1,0]
	v_pk_mul_f32 v[36:37], v[36:37], v[52:53] op_sel_hi:[1,0]
	v_pk_mul_f32 v[38:39], v[38:39], v[52:53] op_sel_hi:[1,0]
	v_pk_mul_f32 v[32:33], v[32:33], v[52:53] op_sel_hi:[1,0]
	v_pk_mul_f32 v[34:35], v[34:35], v[52:53] op_sel_hi:[1,0]
	v_mul_f32_e32 v52, 0xbfb8aa3b, v44
	v_mul_f32_e32 v53, 0xbfb8aa3b, v45
	v_mul_f32_e32 v54, 0xbfb8aa3b, v46
	v_mul_f32_e32 v55, 0xbfb8aa3b, v47
	v_mul_f32_e32 v56, 0xbfb8aa3b, v40
	v_mul_f32_e32 v57, 0xbfb8aa3b, v41
	v_mul_f32_e32 v58, 0xbfb8aa3b, v42
	v_mul_f32_e32 v59, 0xbfb8aa3b, v43
	v_exp_f32_e32 v52, v52
	v_exp_f32_e32 v53, v53
	v_exp_f32_e32 v54, v54
	v_exp_f32_e32 v55, v55
	v_exp_f32_e32 v56, v56
	v_exp_f32_e32 v57, v57
	v_exp_f32_e32 v58, v58
	v_exp_f32_e32 v59, v59
	v_add_f32_e32 v52, 1.0, v52
	v_add_f32_e32 v53, 1.0, v53
	v_add_f32_e32 v54, 1.0, v54
	v_add_f32_e32 v55, 1.0, v55
	v_add_f32_e32 v56, 1.0, v56
	v_add_f32_e32 v57, 1.0, v57
	v_add_f32_e32 v58, 1.0, v58
	v_add_f32_e32 v59, 1.0, v59
	v_rcp_f32_e32 v52, v52
	v_rcp_f32_e32 v53, v53
	v_rcp_f32_e32 v54, v54
	v_rcp_f32_e32 v55, v55
	v_rcp_f32_e32 v56, v56
	v_rcp_f32_e32 v57, v57
	v_rcp_f32_e32 v58, v58
	v_rcp_f32_e32 v59, v59
	v_pk_mul_f32 v[44:45], v[44:45], v[52:53]
	v_pk_mul_f32 v[46:47], v[46:47], v[54:55]
	v_pk_mul_f32 v[40:41], v[40:41], v[56:57]
	v_pk_mul_f32 v[42:43], v[42:43], v[58:59]
	v_pk_mul_f32 v[36:37], v[36:37], v[44:45]
	v_pk_mul_f32 v[38:39], v[38:39], v[46:47]
	v_pk_mul_f32 v[40:41], v[32:33], v[40:41]
	v_pk_mul_f32 v[42:43], v[34:35], v[42:43]
	v_cvt_pk_bf16_f32 v32, v36, v37
	v_cvt_pk_bf16_f32 v33, v38, v39
	v_cvt_pk_bf16_f32 v34, v40, v41
	v_cvt_pk_bf16_f32 v35, v42, v43
	global_store_dwordx4 v[50:51], v[32:35], off nt
	s_nop 1
	s_nop 0
	v_add_u32_e32 v32, 0xb0, v164
	v_ashrrev_i32_e32 v33, 31, v32
	v_lshl_add_u64 v[32:33], v[32:33], 2, s[6:7]
	v_fmamk_f32 v34, v194, 0x3a800000, v171
	v_mul_f32_e32 v35, 0x4b800000, v34
	v_cmp_gt_f32_e32 vcc, s40, v34
	s_nop 1
	v_cndmask_b32_e32 v34, v34, v35, vcc
	v_rsq_f32_e32 v36, v34
	v_lshl_add_u64 v[34:35], s[18:19], 0, v[152:153]
	v_lshl_add_u64 v[34:35], v[34:35], 0, v[136:137]
	v_mul_f32_e32 v37, 0x45800000, v36
	v_cndmask_b32_e32 v36, v36, v37, vcc
	v_pk_mul_f32 v[28:29], v[28:29], v[36:37] op_sel_hi:[1,0]
	v_pk_mul_f32 v[30:31], v[30:31], v[36:37] op_sel_hi:[1,0]
	v_pk_mul_f32 v[24:25], v[24:25], v[36:37] op_sel_hi:[1,0]
	v_pk_mul_f32 v[26:27], v[26:27], v[36:37] op_sel_hi:[1,0]
	v_pk_mul_f32 v[20:21], v[20:21], v[36:37] op_sel_hi:[1,0]
	v_pk_mul_f32 v[22:23], v[22:23], v[36:37] op_sel_hi:[1,0]
	v_pk_mul_f32 v[16:17], v[16:17], v[36:37] op_sel_hi:[1,0]
	v_pk_mul_f32 v[18:19], v[18:19], v[36:37] op_sel_hi:[1,0]
	v_mul_f32_e32 v36, 0xbfb8aa3b, v28
	v_mul_f32_e32 v37, 0xbfb8aa3b, v29
	v_mul_f32_e32 v38, 0xbfb8aa3b, v30
	v_mul_f32_e32 v39, 0xbfb8aa3b, v31
	v_mul_f32_e32 v40, 0xbfb8aa3b, v24
	v_mul_f32_e32 v41, 0xbfb8aa3b, v25
	v_mul_f32_e32 v42, 0xbfb8aa3b, v26
	v_mul_f32_e32 v43, 0xbfb8aa3b, v27
	v_exp_f32_e32 v36, v36
	v_exp_f32_e32 v37, v37
	v_exp_f32_e32 v38, v38
	v_exp_f32_e32 v39, v39
	v_exp_f32_e32 v40, v40
	v_exp_f32_e32 v41, v41
	v_exp_f32_e32 v42, v42
	v_exp_f32_e32 v43, v43
	v_add_f32_e32 v36, 1.0, v36
	v_add_f32_e32 v37, 1.0, v37
	v_add_f32_e32 v38, 1.0, v38
	v_add_f32_e32 v39, 1.0, v39
	v_add_f32_e32 v40, 1.0, v40
	v_add_f32_e32 v41, 1.0, v41
	v_add_f32_e32 v42, 1.0, v42
	v_add_f32_e32 v43, 1.0, v43
	v_rcp_f32_e32 v36, v36
	v_rcp_f32_e32 v37, v37
	v_rcp_f32_e32 v38, v38
	v_rcp_f32_e32 v39, v39
	v_rcp_f32_e32 v40, v40
	v_rcp_f32_e32 v41, v41
	v_rcp_f32_e32 v42, v42
	v_rcp_f32_e32 v43, v43
	v_pk_mul_f32 v[28:29], v[28:29], v[36:37]
	v_pk_mul_f32 v[30:31], v[30:31], v[38:39]
	v_pk_mul_f32 v[24:25], v[24:25], v[40:41]
	v_pk_mul_f32 v[26:27], v[26:27], v[42:43]
	v_pk_mul_f32 v[20:21], v[20:21], v[28:29]
	v_pk_mul_f32 v[22:23], v[22:23], v[30:31]
	v_pk_mul_f32 v[24:25], v[16:17], v[24:25]
	v_pk_mul_f32 v[26:27], v[18:19], v[26:27]
	v_cvt_pk_bf16_f32 v16, v20, v21
	v_cvt_pk_bf16_f32 v17, v22, v23
	v_cvt_pk_bf16_f32 v18, v24, v25
	v_cvt_pk_bf16_f32 v19, v26, v27
	global_store_dwordx4 v[34:35], v[16:19], off nt
	s_nop 1
	s_andn2_b64 vcc, exec, s[2:3]
	s_mov_b64 s[2:3], -1
	v_fmamk_f32 v16, v195, 0x3a800000, v171
	v_mul_f32_e32 v17, 0x4b800000, v16
	v_cmp_gt_f32_e64 s[4:5], s40, v16
	s_nop 1
	v_cndmask_b32_e64 v16, v16, v17, s[4:5]
	v_rsq_f32_e32 v18, v16
	v_lshl_add_u64 v[16:17], s[18:19], 0, v[154:155]
	v_lshl_add_u64 v[16:17], v[16:17], 0, v[136:137]
	v_mul_f32_e32 v19, 0x45800000, v18
	v_cndmask_b32_e64 v18, v18, v19, s[4:5]
	v_pk_mul_f32 v[12:13], v[12:13], v[18:19] op_sel_hi:[1,0]
	v_pk_mul_f32 v[14:15], v[14:15], v[18:19] op_sel_hi:[1,0]
	v_pk_mul_f32 v[8:9], v[8:9], v[18:19] op_sel_hi:[1,0]
	v_pk_mul_f32 v[10:11], v[10:11], v[18:19] op_sel_hi:[1,0]
	v_pk_mul_f32 v[4:5], v[4:5], v[18:19] op_sel_hi:[1,0]
	v_pk_mul_f32 v[6:7], v[6:7], v[18:19] op_sel_hi:[1,0]
	v_pk_mul_f32 v[0:1], v[0:1], v[18:19] op_sel_hi:[1,0]
	v_pk_mul_f32 v[2:3], v[2:3], v[18:19] op_sel_hi:[1,0]
	v_mul_f32_e32 v18, 0xbfb8aa3b, v12
	v_mul_f32_e32 v19, 0xbfb8aa3b, v13
	v_mul_f32_e32 v20, 0xbfb8aa3b, v14
	v_mul_f32_e32 v21, 0xbfb8aa3b, v15
	v_mul_f32_e32 v22, 0xbfb8aa3b, v8
	v_mul_f32_e32 v23, 0xbfb8aa3b, v9
	v_mul_f32_e32 v24, 0xbfb8aa3b, v10
	v_mul_f32_e32 v25, 0xbfb8aa3b, v11
	v_exp_f32_e32 v18, v18
	v_exp_f32_e32 v19, v19
	v_exp_f32_e32 v20, v20
	v_exp_f32_e32 v21, v21
	v_exp_f32_e32 v22, v22
	v_exp_f32_e32 v23, v23
	v_exp_f32_e32 v24, v24
	v_exp_f32_e32 v25, v25
	v_add_f32_e32 v18, 1.0, v18
	v_add_f32_e32 v19, 1.0, v19
	v_add_f32_e32 v20, 1.0, v20
	v_add_f32_e32 v21, 1.0, v21
	v_add_f32_e32 v22, 1.0, v22
	v_add_f32_e32 v23, 1.0, v23
	v_add_f32_e32 v24, 1.0, v24
	v_add_f32_e32 v25, 1.0, v25
	v_rcp_f32_e32 v18, v18
	v_rcp_f32_e32 v19, v19
	v_rcp_f32_e32 v20, v20
	v_rcp_f32_e32 v21, v21
	v_rcp_f32_e32 v22, v22
	v_rcp_f32_e32 v23, v23
	v_rcp_f32_e32 v24, v24
	v_rcp_f32_e32 v25, v25
	v_pk_mul_f32 v[12:13], v[12:13], v[18:19]
	v_pk_mul_f32 v[14:15], v[14:15], v[20:21]
	v_pk_mul_f32 v[8:9], v[8:9], v[22:23]
	v_pk_mul_f32 v[10:11], v[10:11], v[24:25]
	v_pk_mul_f32 v[4:5], v[4:5], v[12:13]
	v_pk_mul_f32 v[6:7], v[6:7], v[14:15]
	v_pk_mul_f32 v[8:9], v[0:1], v[8:9]
	v_pk_mul_f32 v[10:11], v[2:3], v[10:11]
	v_cvt_pk_bf16_f32 v0, v4, v5
	v_cvt_pk_bf16_f32 v1, v6, v7
	v_cvt_pk_bf16_f32 v2, v8, v9
	v_cvt_pk_bf16_f32 v3, v10, v11
	global_store_dwordx4 v[16:17], v[0:3], off nt
	s_cbranch_vccnz .LBB0_1623
	s_andn2_b64 vcc, exec, s[0:1]
	s_cbranch_vccnz .LBB0_1622
	s_barrier
	s_branch .LBB0_1622
